# v52: barrier poll loop keeps two polls of the top counter in flight (no sleep) for lower detection latency
# baseline (speedup 1.0000x reference)
; __device__ __forceinline__ unsigned xb_ld(unsigned* p)              { return __hip_atomic_load(p, __ATOMIC_RELAXED, __HIP_MEMORY_SCOPE_AGENT); }
; __device__ __forceinline__ unsigned xb_add(unsigned* p, unsigned v) { return __hip_atomic_fetch_add(p, v, __ATOMIC_RELAXED, __HIP_MEMORY_SCOPE_AGENT); }
; #define XB_SPIN(cond, bar) do { unsigned _sp = 0; while (cond) { __builtin_amdgcn_s_sleep(1); \
;     if ((++_sp & 255u) == 0u) { if (xb_ld(&(bar)[XB_TMO])) break; if (_sp > XB_SPIN_CAP) { atomicAdd(&(bar)[XB_TMO], 1u); break; } } } } while (0)
; __device__ __forceinline__ void xcd_barrier(const XcdBarrier& b) {
;     ...
;             const unsigned og = xb_add(&bar[XB_TOP], 1u);
;             const unsigned tg = og / nx;
;             if (og + 1u == (tg + 1u) * nx) xb_add(&bar[XB_TOPGEN], 1u);
;             else XB_SPIN(xb_ld(&bar[XB_TOPGEN]) == tg, bar);
.Lfb0_spin0:
	s_mov_b32 s3, 0
	global_load_dword v5, v4, s[4:5] sc1
.Lfb0_spin:
	global_load_dword v6, v4, s[4:5] sc1
	s_waitcnt vmcnt(1)
	v_cmp_ge_u32_e32 vcc, v5, v3
	s_cbranch_vccnz .Lfb0_done
	global_load_dword v5, v4, s[4:5] sc1
	s_waitcnt vmcnt(1)
	v_cmp_ge_u32_e32 vcc, v6, v3
	s_cbranch_vccnz .Lfb0_done
	s_add_u32 s3, s3, 1
	s_cmp_lt_u32 s3, 0x100000
	s_cbranch_scc1 .Lfb0_spin

; __device__ __forceinline__ unsigned xb_ld(unsigned* p)              { return __hip_atomic_load(p, __ATOMIC_RELAXED, __HIP_MEMORY_SCOPE_AGENT); }
; __device__ __forceinline__ unsigned xb_add(unsigned* p, unsigned v) { return __hip_atomic_fetch_add(p, v, __ATOMIC_RELAXED, __HIP_MEMORY_SCOPE_AGENT); }
; #define XB_SPIN(cond, bar) do { unsigned _sp = 0; while (cond) { __builtin_amdgcn_s_sleep(1); \
;     if ((++_sp & 255u) == 0u) { if (xb_ld(&(bar)[XB_TMO])) break; if (_sp > XB_SPIN_CAP) { atomicAdd(&(bar)[XB_TMO], 1u); break; } } } } while (0)
; __device__ __forceinline__ void xcd_barrier(const XcdBarrier& b) {
;     ...
;             const unsigned og = xb_add(&bar[XB_TOP], 1u);
;             const unsigned tg = og / nx;
;             if (og + 1u == (tg + 1u) * nx) xb_add(&bar[XB_TOPGEN], 1u);
;             else XB_SPIN(xb_ld(&bar[XB_TOPGEN]) == tg, bar);
.Lfb2_spin0:
	s_mov_b32 s6, 0
	global_load_dword v5, v4, s[4:5] sc1
.Lfb2_spin:
	global_load_dword v6, v4, s[4:5] sc1
	s_waitcnt vmcnt(1)
	v_cmp_ge_u32_e32 vcc, v5, v3
	s_cbranch_vccnz .Lfb2_done
	global_load_dword v5, v4, s[4:5] sc1
	s_waitcnt vmcnt(1)
	v_cmp_ge_u32_e32 vcc, v6, v3
	s_cbranch_vccnz .Lfb2_done
	s_add_u32 s6, s6, 1
	s_cmp_lt_u32 s6, 0x100000
	s_cbranch_scc1 .Lfb2_spin

; __device__ __forceinline__ unsigned xb_ld(unsigned* p)              { return __hip_atomic_load(p, __ATOMIC_RELAXED, __HIP_MEMORY_SCOPE_AGENT); }
; __device__ __forceinline__ unsigned xb_add(unsigned* p, unsigned v) { return __hip_atomic_fetch_add(p, v, __ATOMIC_RELAXED, __HIP_MEMORY_SCOPE_AGENT); }
; #define XB_SPIN(cond, bar) do { unsigned _sp = 0; while (cond) { __builtin_amdgcn_s_sleep(1); \
;     if ((++_sp & 255u) == 0u) { if (xb_ld(&(bar)[XB_TMO])) break; if (_sp > XB_SPIN_CAP) { atomicAdd(&(bar)[XB_TMO], 1u); break; } } } } while (0)
; __device__ __forceinline__ void xcd_barrier(const XcdBarrier& b) {
;     ...
;             const unsigned og = xb_add(&bar[XB_TOP], 1u);
;             const unsigned tg = og / nx;
;             if (og + 1u == (tg + 1u) * nx) xb_add(&bar[XB_TOPGEN], 1u);
;             else XB_SPIN(xb_ld(&bar[XB_TOPGEN]) == tg, bar);
.Lfb6_spin0:
	s_mov_b32 s3, 0
	global_load_dword v5, v4, s[8:9] sc1
.Lfb6_spin:
	global_load_dword v6, v4, s[8:9] sc1
	s_waitcnt vmcnt(1)
	v_cmp_ge_u32_e32 vcc, v5, v3
	s_cbranch_vccnz .Lfb6_done
	global_load_dword v5, v4, s[8:9] sc1
	s_waitcnt vmcnt(1)
	v_cmp_ge_u32_e32 vcc, v6, v3
	s_cbranch_vccnz .Lfb6_done
	s_add_u32 s3, s3, 1
	s_cmp_lt_u32 s3, 0x100000
	s_cbranch_scc1 .Lfb6_spin

; __device__ __forceinline__ unsigned xb_ld(unsigned* p)              { return __hip_atomic_load(p, __ATOMIC_RELAXED, __HIP_MEMORY_SCOPE_AGENT); }
; __device__ __forceinline__ unsigned xb_add(unsigned* p, unsigned v) { return __hip_atomic_fetch_add(p, v, __ATOMIC_RELAXED, __HIP_MEMORY_SCOPE_AGENT); }
; #define XB_SPIN(cond, bar) do { unsigned _sp = 0; while (cond) { __builtin_amdgcn_s_sleep(1); \
;     if ((++_sp & 255u) == 0u) { if (xb_ld(&(bar)[XB_TMO])) break; if (_sp > XB_SPIN_CAP) { atomicAdd(&(bar)[XB_TMO], 1u); break; } } } } while (0)
; __device__ __forceinline__ void xcd_barrier(const XcdBarrier& b) {
;     ...
;             const unsigned og = xb_add(&bar[XB_TOP], 1u);
;             const unsigned tg = og / nx;
;             if (og + 1u == (tg + 1u) * nx) xb_add(&bar[XB_TOPGEN], 1u);
;             else XB_SPIN(xb_ld(&bar[XB_TOPGEN]) == tg, bar);
.Lfb8_spin0:
	s_mov_b32 s8, 0
	global_load_dword v4, v1, s[6:7] sc1
.Lfb8_spin:
	global_load_dword v5, v1, s[6:7] sc1
	s_waitcnt vmcnt(1)
	v_cmp_ge_u32_e32 vcc, v4, v3
	s_cbranch_vccnz .Lfb8_done
	global_load_dword v4, v1, s[6:7] sc1
	s_waitcnt vmcnt(1)
	v_cmp_ge_u32_e32 vcc, v5, v3
	s_cbranch_vccnz .Lfb8_done
	s_add_u32 s8, s8, 1
	s_cmp_lt_u32 s8, 0x100000
	s_cbranch_scc1 .Lfb8_spin

; __device__ __forceinline__ unsigned xb_ld(unsigned* p)              { return __hip_atomic_load(p, __ATOMIC_RELAXED, __HIP_MEMORY_SCOPE_AGENT); }
; __device__ __forceinline__ unsigned xb_add(unsigned* p, unsigned v) { return __hip_atomic_fetch_add(p, v, __ATOMIC_RELAXED, __HIP_MEMORY_SCOPE_AGENT); }
; #define XB_SPIN(cond, bar) do { unsigned _sp = 0; while (cond) { __builtin_amdgcn_s_sleep(1); \
;     if ((++_sp & 255u) == 0u) { if (xb_ld(&(bar)[XB_TMO])) break; if (_sp > XB_SPIN_CAP) { atomicAdd(&(bar)[XB_TMO], 1u); break; } } } } while (0)
; __device__ __forceinline__ void xcd_barrier(const XcdBarrier& b) {
;     ...
;             const unsigned og = xb_add(&bar[XB_TOP], 1u);
;             const unsigned tg = og / nx;
;             if (og + 1u == (tg + 1u) * nx) xb_add(&bar[XB_TOPGEN], 1u);
;             else XB_SPIN(xb_ld(&bar[XB_TOPGEN]) == tg, bar);
.Lfb9_spin0:
	s_mov_b32 s8, 0
	global_load_dword v3, v2, s[6:7] sc1
.Lfb9_spin:
	global_load_dword v4, v2, s[6:7] sc1
	s_waitcnt vmcnt(1)
	v_cmp_ge_u32_e32 vcc, v3, v1
	s_cbranch_vccnz .Lfb9_done
	global_load_dword v3, v2, s[6:7] sc1
	s_waitcnt vmcnt(1)
	v_cmp_ge_u32_e32 vcc, v4, v1
	s_cbranch_vccnz .Lfb9_done
	s_add_u32 s8, s8, 1
	s_cmp_lt_u32 s8, 0x100000
	s_cbranch_scc1 .Lfb9_spin
